# mix generic GEMM-unit epilogue: row-major 16B gate loads and output stores via wave-private LDS transpose
# speedup vs baseline: 1.0097x; 1.0097x over previous
.LBB0_1086:
	s_waitcnt vmcnt(0)
	s_mov_b64 s[4:5], -1
	s_and_b64 vcc, exec, s[20:21]
	s_barrier
	s_cbranch_vccz .LBB0_1152
	v_lshrrev_b32_e32 v146, 6, v144
	s_movk_i32 s5, 0x90
	s_nop 0
	v_readfirstlane_b32 s4, v146
	s_mul_i32 s4, s4, 0x2400
	s_add_i32 s4, s4, 32
	v_and_b32_e32 v146, 63, v144
	v_lshrrev_b32_e32 v147, 3, v146
	v_and_b32_e32 v148, 7, v146
	v_lshlrev_b32_e32 v148, 4, v148
	v_mad_u32_u24 v0, v147, s5, v148
	v_add_u32_e32 v0, s4, v0
	v_and_b32_e32 v149, 4, v145
	v_lshlrev_b32_e32 v1, 1, v149
	v_mad_u32_u24 v1, v161, s5, v1
	v_add_u32_e32 v1, s4, v1
	v_and_b32_e32 v150, 0xc0, v144
	v_add_u32_e32 v3, v150, v149
	v_lshlrev_b32_e32 v3, 2, v3
	v_lshl_add_u32 v150, v150, 1, v148
	v_lshrrev_b32_e32 v151, 1, v144
	v_and_b32_e32 v151, 0x80, v151
	v_add_u32_e32 v151, v151, v147
	v_mad_u32_u24 v2, v151, s92, v150
	v_lshl_add_u32 v5, v151, 11, v150
	v_readlane_b32 s70, v254, 8
	v_readlane_b32 s71, v254, 9
	s_mul_i32 s4, s68, 0xa00
	s_lshl_b32 s5, s14, 1
	s_add_u32 s4, s4, s5
	s_add_u32 s70, s70, s4
	s_addc_u32 s71, s71, 0
	s_lshl_b32 s4, s68, 11
	s_lshl_b32 s5, s12, 1
	s_add_u32 s4, s4, s5
	s_add_u32 s72, s46, s4
	s_addc_u32 s73, s47, 0
	s_cmp_lg_u64 s[0:1], 0
	s_cbranch_scc1 .Lgepi_scale
	s_add_u32 s74, s70, 0x0
	s_addc_u32 s75, s71, 0
	global_load_dwordx4 v[146:149], v2, s[74:75]
	s_add_u32 s74, s70, 0x5000
	s_addc_u32 s75, s71, 0
	global_load_dwordx4 v[150:153], v2, s[74:75]
	s_add_u32 s74, s70, 0xa000
	s_addc_u32 s75, s71, 0
	global_load_dwordx4 v[154:157], v2, s[74:75]
	s_add_u32 s74, s70, 0xf000
	s_addc_u32 s75, s71, 0
	global_load_dwordx4 v[158:161], v2, s[74:75]
	s_add_u32 s74, s70, 0x14000
	s_addc_u32 s75, s71, 0
	global_load_dwordx4 v[162:165], v2, s[74:75]
	s_add_u32 s74, s70, 0x19000
	s_addc_u32 s75, s71, 0
	global_load_dwordx4 v[166:169], v2, s[74:75]
	s_add_u32 s74, s70, 0x1e000
	s_addc_u32 s75, s71, 0
	global_load_dwordx4 v[170:173], v2, s[74:75]
	s_add_u32 s74, s70, 0x23000
	s_addc_u32 s75, s71, 0
	global_load_dwordx4 v[174:177], v2, s[74:75]
	s_add_u32 s74, s70, 0x28000
	s_addc_u32 s75, s71, 0
	global_load_dwordx4 v[178:181], v2, s[74:75]
	s_add_u32 s74, s70, 0x2d000
	s_addc_u32 s75, s71, 0
	global_load_dwordx4 v[182:185], v2, s[74:75]
	s_add_u32 s74, s70, 0x32000
	s_addc_u32 s75, s71, 0
	global_load_dwordx4 v[186:189], v2, s[74:75]
	s_add_u32 s74, s70, 0x37000
	s_addc_u32 s75, s71, 0
	global_load_dwordx4 v[190:193], v2, s[74:75]
	s_add_u32 s74, s70, 0x3c000
	s_addc_u32 s75, s71, 0
	global_load_dwordx4 v[194:197], v2, s[74:75]
	s_add_u32 s74, s70, 0x41000
	s_addc_u32 s75, s71, 0
	global_load_dwordx4 v[198:201], v2, s[74:75]
	s_add_u32 s74, s70, 0x46000
	s_addc_u32 s75, s71, 0
	global_load_dwordx4 v[202:205], v2, s[74:75]
	s_add_u32 s74, s70, 0x4b000
	s_addc_u32 s75, s71, 0
	global_load_dwordx4 v[206:209], v2, s[74:75]
	s_waitcnt vmcnt(15)
	ds_write_b128 v0, v[146:149]
	s_waitcnt vmcnt(14)
	ds_write_b128 v0, v[150:153] offset:1152
	s_waitcnt vmcnt(13)
	ds_write_b128 v0, v[154:157] offset:2304
	s_waitcnt vmcnt(12)
	ds_write_b128 v0, v[158:161] offset:3456
	s_waitcnt vmcnt(11)
	ds_write_b128 v0, v[162:165] offset:4608
	s_waitcnt vmcnt(10)
	ds_write_b128 v0, v[166:169] offset:5760
	s_waitcnt vmcnt(9)
	ds_write_b128 v0, v[170:173] offset:6912
	s_waitcnt vmcnt(8)
	ds_write_b128 v0, v[174:177] offset:8064
	s_waitcnt lgkmcnt(7)
	ds_read_b64 v[146:147], v1
	ds_read_b64 v[148:149], v1 offset:16
	ds_read_b64 v[150:151], v1 offset:32
	ds_read_b64 v[152:153], v1 offset:48
	ds_read_b64 v[154:155], v1 offset:64
	ds_read_b64 v[156:157], v1 offset:80
	ds_read_b64 v[158:159], v1 offset:96
	ds_read_b64 v[160:161], v1 offset:112
	s_waitcnt lgkmcnt(7)
	v_and_b32_e32 v3, 0xffff0000, v146
	v_lshlrev_b32_e32 v2, 16, v146
	v_pk_mul_f32 v[118:119], v[118:119], v[2:3]
	v_and_b32_e32 v3, 0xffff0000, v147
	v_lshlrev_b32_e32 v2, 16, v147
	v_pk_mul_f32 v[120:121], v[120:121], v[2:3]
	v_cvt_pk_bf16_f32 v146, v118, v119
	v_cvt_pk_bf16_f32 v147, v120, v121
	ds_write_b64 v1, v[146:147]
	s_waitcnt lgkmcnt(7)
	v_and_b32_e32 v3, 0xffff0000, v148
	v_lshlrev_b32_e32 v2, 16, v148
	v_pk_mul_f32 v[122:123], v[122:123], v[2:3]
	v_and_b32_e32 v3, 0xffff0000, v149
	v_lshlrev_b32_e32 v2, 16, v149
	v_pk_mul_f32 v[124:125], v[124:125], v[2:3]
	v_cvt_pk_bf16_f32 v148, v122, v123
	v_cvt_pk_bf16_f32 v149, v124, v125
	ds_write_b64 v1, v[148:149] offset:16
	s_waitcnt lgkmcnt(7)
	v_and_b32_e32 v3, 0xffff0000, v150
	v_lshlrev_b32_e32 v2, 16, v150
	v_pk_mul_f32 v[126:127], v[126:127], v[2:3]
	v_and_b32_e32 v3, 0xffff0000, v151
	v_lshlrev_b32_e32 v2, 16, v151
	v_pk_mul_f32 v[128:129], v[128:129], v[2:3]
	v_cvt_pk_bf16_f32 v150, v126, v127
	v_cvt_pk_bf16_f32 v151, v128, v129
	ds_write_b64 v1, v[150:151] offset:32
	s_waitcnt lgkmcnt(7)
	v_and_b32_e32 v3, 0xffff0000, v152
	v_lshlrev_b32_e32 v2, 16, v152
	v_pk_mul_f32 v[130:131], v[130:131], v[2:3]
	v_and_b32_e32 v3, 0xffff0000, v153
	v_lshlrev_b32_e32 v2, 16, v153
	v_pk_mul_f32 v[132:133], v[132:133], v[2:3]
	v_cvt_pk_bf16_f32 v152, v130, v131
	v_cvt_pk_bf16_f32 v153, v132, v133
	ds_write_b64 v1, v[152:153] offset:48
	s_waitcnt lgkmcnt(7)
	v_and_b32_e32 v3, 0xffff0000, v154
	v_lshlrev_b32_e32 v2, 16, v154
	v_pk_mul_f32 v[102:103], v[102:103], v[2:3]
	v_and_b32_e32 v3, 0xffff0000, v155
	v_lshlrev_b32_e32 v2, 16, v155
	v_pk_mul_f32 v[104:105], v[104:105], v[2:3]
	v_cvt_pk_bf16_f32 v154, v102, v103
	v_cvt_pk_bf16_f32 v155, v104, v105
	ds_write_b64 v1, v[154:155] offset:64
	s_waitcnt lgkmcnt(7)
	v_and_b32_e32 v3, 0xffff0000, v156
	v_lshlrev_b32_e32 v2, 16, v156
	v_pk_mul_f32 v[106:107], v[106:107], v[2:3]
	v_and_b32_e32 v3, 0xffff0000, v157
	v_lshlrev_b32_e32 v2, 16, v157
	v_pk_mul_f32 v[108:109], v[108:109], v[2:3]
	v_cvt_pk_bf16_f32 v156, v106, v107
	v_cvt_pk_bf16_f32 v157, v108, v109
	ds_write_b64 v1, v[156:157] offset:80
	s_waitcnt lgkmcnt(7)
	v_and_b32_e32 v3, 0xffff0000, v158
	v_lshlrev_b32_e32 v2, 16, v158
	v_pk_mul_f32 v[110:111], v[110:111], v[2:3]
	v_and_b32_e32 v3, 0xffff0000, v159
	v_lshlrev_b32_e32 v2, 16, v159
	v_pk_mul_f32 v[112:113], v[112:113], v[2:3]
	v_cvt_pk_bf16_f32 v158, v110, v111
	v_cvt_pk_bf16_f32 v159, v112, v113
	ds_write_b64 v1, v[158:159] offset:96
	s_waitcnt lgkmcnt(7)
	v_and_b32_e32 v3, 0xffff0000, v160
	v_lshlrev_b32_e32 v2, 16, v160
	v_pk_mul_f32 v[114:115], v[114:115], v[2:3]
	v_and_b32_e32 v3, 0xffff0000, v161
	v_lshlrev_b32_e32 v2, 16, v161
	v_pk_mul_f32 v[116:117], v[116:117], v[2:3]
	v_cvt_pk_bf16_f32 v160, v114, v115
	v_cvt_pk_bf16_f32 v161, v116, v117
	ds_write_b64 v1, v[160:161] offset:112
	s_waitcnt lgkmcnt(7)
	ds_read_b64 v[162:163], v1 offset:4608
	ds_read_b64 v[164:165], v1 offset:4624
	ds_read_b64 v[166:167], v1 offset:4640
	ds_read_b64 v[168:169], v1 offset:4656
	ds_read_b64 v[170:171], v1 offset:4672
	ds_read_b64 v[172:173], v1 offset:4688
	ds_read_b64 v[174:175], v1 offset:4704
	ds_read_b64 v[176:177], v1 offset:4720
	s_waitcnt lgkmcnt(7)
	v_and_b32_e32 v3, 0xffff0000, v162
	v_lshlrev_b32_e32 v2, 16, v162
	v_pk_mul_f32 v[86:87], v[86:87], v[2:3]
	v_and_b32_e32 v3, 0xffff0000, v163
	v_lshlrev_b32_e32 v2, 16, v163
	v_pk_mul_f32 v[88:89], v[88:89], v[2:3]
	v_cvt_pk_bf16_f32 v162, v86, v87
	v_cvt_pk_bf16_f32 v163, v88, v89
	ds_write_b64 v1, v[162:163] offset:4608
	s_waitcnt lgkmcnt(7)
	v_and_b32_e32 v3, 0xffff0000, v164
	v_lshlrev_b32_e32 v2, 16, v164
	v_pk_mul_f32 v[90:91], v[90:91], v[2:3]
	v_and_b32_e32 v3, 0xffff0000, v165
	v_lshlrev_b32_e32 v2, 16, v165
	v_pk_mul_f32 v[92:93], v[92:93], v[2:3]
	v_cvt_pk_bf16_f32 v164, v90, v91
	v_cvt_pk_bf16_f32 v165, v92, v93
	ds_write_b64 v1, v[164:165] offset:4624
	s_waitcnt lgkmcnt(7)
	v_and_b32_e32 v3, 0xffff0000, v166
	v_lshlrev_b32_e32 v2, 16, v166
	v_pk_mul_f32 v[94:95], v[94:95], v[2:3]
	v_and_b32_e32 v3, 0xffff0000, v167
	v_lshlrev_b32_e32 v2, 16, v167
	v_pk_mul_f32 v[96:97], v[96:97], v[2:3]
	v_cvt_pk_bf16_f32 v166, v94, v95
	v_cvt_pk_bf16_f32 v167, v96, v97
	ds_write_b64 v1, v[166:167] offset:4640
	s_waitcnt lgkmcnt(7)
	v_and_b32_e32 v3, 0xffff0000, v168
	v_lshlrev_b32_e32 v2, 16, v168
	v_pk_mul_f32 v[98:99], v[98:99], v[2:3]
	v_and_b32_e32 v3, 0xffff0000, v169
	v_lshlrev_b32_e32 v2, 16, v169
	v_pk_mul_f32 v[100:101], v[100:101], v[2:3]
	v_cvt_pk_bf16_f32 v168, v98, v99
	v_cvt_pk_bf16_f32 v169, v100, v101
	ds_write_b64 v1, v[168:169] offset:4656
	s_waitcnt lgkmcnt(7)
	v_and_b32_e32 v3, 0xffff0000, v170
	v_lshlrev_b32_e32 v2, 16, v170
	v_pk_mul_f32 v[70:71], v[70:71], v[2:3]
	v_and_b32_e32 v3, 0xffff0000, v171
	v_lshlrev_b32_e32 v2, 16, v171
	v_pk_mul_f32 v[72:73], v[72:73], v[2:3]
	v_cvt_pk_bf16_f32 v170, v70, v71
	v_cvt_pk_bf16_f32 v171, v72, v73
	ds_write_b64 v1, v[170:171] offset:4672
	s_waitcnt lgkmcnt(7)
	v_and_b32_e32 v3, 0xffff0000, v172
	v_lshlrev_b32_e32 v2, 16, v172
	v_pk_mul_f32 v[74:75], v[74:75], v[2:3]
	v_and_b32_e32 v3, 0xffff0000, v173
	v_lshlrev_b32_e32 v2, 16, v173
	v_pk_mul_f32 v[76:77], v[76:77], v[2:3]
	v_cvt_pk_bf16_f32 v172, v74, v75
	v_cvt_pk_bf16_f32 v173, v76, v77
	ds_write_b64 v1, v[172:173] offset:4688
	s_waitcnt lgkmcnt(7)
	v_and_b32_e32 v3, 0xffff0000, v174
	v_lshlrev_b32_e32 v2, 16, v174
	v_pk_mul_f32 v[78:79], v[78:79], v[2:3]
	v_and_b32_e32 v3, 0xffff0000, v175
	v_lshlrev_b32_e32 v2, 16, v175
	v_pk_mul_f32 v[80:81], v[80:81], v[2:3]
	v_cvt_pk_bf16_f32 v174, v78, v79
	v_cvt_pk_bf16_f32 v175, v80, v81
	ds_write_b64 v1, v[174:175] offset:4704
	s_waitcnt lgkmcnt(7)
	v_and_b32_e32 v3, 0xffff0000, v176
	v_lshlrev_b32_e32 v2, 16, v176
	v_pk_mul_f32 v[82:83], v[82:83], v[2:3]
	v_and_b32_e32 v3, 0xffff0000, v177
	v_lshlrev_b32_e32 v2, 16, v177
	v_pk_mul_f32 v[84:85], v[84:85], v[2:3]
	v_cvt_pk_bf16_f32 v176, v82, v83
	v_cvt_pk_bf16_f32 v177, v84, v85
	ds_write_b64 v1, v[176:177] offset:4720
	s_waitcnt lgkmcnt(7)
	ds_read_b128 v[146:149], v0
	ds_read_b128 v[150:153], v0 offset:1152
	ds_read_b128 v[154:157], v0 offset:2304
	ds_read_b128 v[158:161], v0 offset:3456
	ds_read_b128 v[162:165], v0 offset:4608
	ds_read_b128 v[166:169], v0 offset:5760
	ds_read_b128 v[170:173], v0 offset:6912
	ds_read_b128 v[174:177], v0 offset:8064
	s_add_u32 s74, s72, 0x0
	s_addc_u32 s75, s73, 0
	s_waitcnt lgkmcnt(7)
	global_store_dwordx4 v5, v[146:149], s[74:75]
	s_add_u32 s74, s72, 0x4000
	s_addc_u32 s75, s73, 0
	s_waitcnt lgkmcnt(6)
	global_store_dwordx4 v5, v[150:153], s[74:75]
	s_add_u32 s74, s72, 0x8000
	s_addc_u32 s75, s73, 0
	s_waitcnt lgkmcnt(5)
	global_store_dwordx4 v5, v[154:157], s[74:75]
	s_add_u32 s74, s72, 0xc000
	s_addc_u32 s75, s73, 0
	s_waitcnt lgkmcnt(4)
	global_store_dwordx4 v5, v[158:161], s[74:75]
	s_add_u32 s74, s72, 0x10000
	s_addc_u32 s75, s73, 0
	s_waitcnt lgkmcnt(3)
	global_store_dwordx4 v5, v[162:165], s[74:75]
	s_add_u32 s74, s72, 0x14000
	s_addc_u32 s75, s73, 0
	s_waitcnt lgkmcnt(2)
	global_store_dwordx4 v5, v[166:169], s[74:75]
	s_add_u32 s74, s72, 0x18000
	s_addc_u32 s75, s73, 0
	s_waitcnt lgkmcnt(1)
	global_store_dwordx4 v5, v[170:173], s[74:75]
	s_add_u32 s74, s72, 0x1c000
	s_addc_u32 s75, s73, 0
	s_waitcnt lgkmcnt(0)
	global_store_dwordx4 v5, v[174:177], s[74:75]
	s_waitcnt vmcnt(15)
	ds_write_b128 v0, v[178:181]
	s_waitcnt vmcnt(14)
	ds_write_b128 v0, v[182:185] offset:1152
	s_waitcnt vmcnt(13)
	ds_write_b128 v0, v[186:189] offset:2304
	s_waitcnt vmcnt(12)
	ds_write_b128 v0, v[190:193] offset:3456
	s_waitcnt vmcnt(11)
	ds_write_b128 v0, v[194:197] offset:4608
	s_waitcnt vmcnt(10)
	ds_write_b128 v0, v[198:201] offset:5760
	s_waitcnt vmcnt(9)
	ds_write_b128 v0, v[202:205] offset:6912
	s_waitcnt vmcnt(8)
	ds_write_b128 v0, v[206:209] offset:8064
	s_waitcnt lgkmcnt(7)
	ds_read_b64 v[178:179], v1
	ds_read_b64 v[180:181], v1 offset:16
	ds_read_b64 v[182:183], v1 offset:32
	ds_read_b64 v[184:185], v1 offset:48
	ds_read_b64 v[186:187], v1 offset:64
	ds_read_b64 v[188:189], v1 offset:80
	ds_read_b64 v[190:191], v1 offset:96
	ds_read_b64 v[192:193], v1 offset:112
	s_waitcnt lgkmcnt(7)
	v_and_b32_e32 v3, 0xffff0000, v178
	v_lshlrev_b32_e32 v2, 16, v178
	v_pk_mul_f32 v[54:55], v[54:55], v[2:3]
	v_and_b32_e32 v3, 0xffff0000, v179
	v_lshlrev_b32_e32 v2, 16, v179
	v_pk_mul_f32 v[56:57], v[56:57], v[2:3]
	v_cvt_pk_bf16_f32 v178, v54, v55
	v_cvt_pk_bf16_f32 v179, v56, v57
	ds_write_b64 v1, v[178:179]
	s_waitcnt lgkmcnt(7)
	v_and_b32_e32 v3, 0xffff0000, v180
	v_lshlrev_b32_e32 v2, 16, v180
	v_pk_mul_f32 v[58:59], v[58:59], v[2:3]
	v_and_b32_e32 v3, 0xffff0000, v181
	v_lshlrev_b32_e32 v2, 16, v181
	v_pk_mul_f32 v[60:61], v[60:61], v[2:3]
	v_cvt_pk_bf16_f32 v180, v58, v59
	v_cvt_pk_bf16_f32 v181, v60, v61
	ds_write_b64 v1, v[180:181] offset:16
	s_waitcnt lgkmcnt(7)
	v_and_b32_e32 v3, 0xffff0000, v182
	v_lshlrev_b32_e32 v2, 16, v182
	v_pk_mul_f32 v[62:63], v[62:63], v[2:3]
	v_and_b32_e32 v3, 0xffff0000, v183
	v_lshlrev_b32_e32 v2, 16, v183
	v_pk_mul_f32 v[64:65], v[64:65], v[2:3]
	v_cvt_pk_bf16_f32 v182, v62, v63
	v_cvt_pk_bf16_f32 v183, v64, v65
	ds_write_b64 v1, v[182:183] offset:32
	s_waitcnt lgkmcnt(7)
	v_and_b32_e32 v3, 0xffff0000, v184
	v_lshlrev_b32_e32 v2, 16, v184
	v_pk_mul_f32 v[66:67], v[66:67], v[2:3]
	v_and_b32_e32 v3, 0xffff0000, v185
	v_lshlrev_b32_e32 v2, 16, v185
	v_pk_mul_f32 v[68:69], v[68:69], v[2:3]
	v_cvt_pk_bf16_f32 v184, v66, v67
	v_cvt_pk_bf16_f32 v185, v68, v69
	ds_write_b64 v1, v[184:185] offset:48
	s_waitcnt lgkmcnt(7)
	v_and_b32_e32 v3, 0xffff0000, v186
	v_lshlrev_b32_e32 v2, 16, v186
	v_pk_mul_f32 v[38:39], v[38:39], v[2:3]
	v_and_b32_e32 v3, 0xffff0000, v187
	v_lshlrev_b32_e32 v2, 16, v187
	v_pk_mul_f32 v[40:41], v[40:41], v[2:3]
	v_cvt_pk_bf16_f32 v186, v38, v39
	v_cvt_pk_bf16_f32 v187, v40, v41
	ds_write_b64 v1, v[186:187] offset:64
	s_waitcnt lgkmcnt(7)
	v_and_b32_e32 v3, 0xffff0000, v188
	v_lshlrev_b32_e32 v2, 16, v188
	v_pk_mul_f32 v[42:43], v[42:43], v[2:3]
	v_and_b32_e32 v3, 0xffff0000, v189
	v_lshlrev_b32_e32 v2, 16, v189
	v_pk_mul_f32 v[44:45], v[44:45], v[2:3]
	v_cvt_pk_bf16_f32 v188, v42, v43
	v_cvt_pk_bf16_f32 v189, v44, v45
	ds_write_b64 v1, v[188:189] offset:80
	s_waitcnt lgkmcnt(7)
	v_and_b32_e32 v3, 0xffff0000, v190
	v_lshlrev_b32_e32 v2, 16, v190
	v_pk_mul_f32 v[46:47], v[46:47], v[2:3]
	v_and_b32_e32 v3, 0xffff0000, v191
	v_lshlrev_b32_e32 v2, 16, v191
	v_pk_mul_f32 v[48:49], v[48:49], v[2:3]
	v_cvt_pk_bf16_f32 v190, v46, v47
	v_cvt_pk_bf16_f32 v191, v48, v49
	ds_write_b64 v1, v[190:191] offset:96
	s_waitcnt lgkmcnt(7)
	v_and_b32_e32 v3, 0xffff0000, v192
	v_lshlrev_b32_e32 v2, 16, v192
	v_pk_mul_f32 v[50:51], v[50:51], v[2:3]
	v_and_b32_e32 v3, 0xffff0000, v193
	v_lshlrev_b32_e32 v2, 16, v193
	v_pk_mul_f32 v[52:53], v[52:53], v[2:3]
	v_cvt_pk_bf16_f32 v192, v50, v51
	v_cvt_pk_bf16_f32 v193, v52, v53
	ds_write_b64 v1, v[192:193] offset:112
	s_waitcnt lgkmcnt(7)
	ds_read_b64 v[194:195], v1 offset:4608
	ds_read_b64 v[196:197], v1 offset:4624
	ds_read_b64 v[198:199], v1 offset:4640
	ds_read_b64 v[200:201], v1 offset:4656
	ds_read_b64 v[202:203], v1 offset:4672
	ds_read_b64 v[204:205], v1 offset:4688
	ds_read_b64 v[206:207], v1 offset:4704
	ds_read_b64 v[208:209], v1 offset:4720
	s_waitcnt lgkmcnt(7)
	v_and_b32_e32 v3, 0xffff0000, v194
	v_lshlrev_b32_e32 v2, 16, v194
	v_pk_mul_f32 v[22:23], v[22:23], v[2:3]
	v_and_b32_e32 v3, 0xffff0000, v195
	v_lshlrev_b32_e32 v2, 16, v195
	v_pk_mul_f32 v[24:25], v[24:25], v[2:3]
	v_cvt_pk_bf16_f32 v194, v22, v23
	v_cvt_pk_bf16_f32 v195, v24, v25
	ds_write_b64 v1, v[194:195] offset:4608
	s_waitcnt lgkmcnt(7)
	v_and_b32_e32 v3, 0xffff0000, v196
	v_lshlrev_b32_e32 v2, 16, v196
	v_pk_mul_f32 v[26:27], v[26:27], v[2:3]
	v_and_b32_e32 v3, 0xffff0000, v197
	v_lshlrev_b32_e32 v2, 16, v197
	v_pk_mul_f32 v[28:29], v[28:29], v[2:3]
	v_cvt_pk_bf16_f32 v196, v26, v27
	v_cvt_pk_bf16_f32 v197, v28, v29
	ds_write_b64 v1, v[196:197] offset:4624
	s_waitcnt lgkmcnt(7)
	v_and_b32_e32 v3, 0xffff0000, v198
	v_lshlrev_b32_e32 v2, 16, v198
	v_pk_mul_f32 v[30:31], v[30:31], v[2:3]
	v_and_b32_e32 v3, 0xffff0000, v199
	v_lshlrev_b32_e32 v2, 16, v199
	v_pk_mul_f32 v[32:33], v[32:33], v[2:3]
	v_cvt_pk_bf16_f32 v198, v30, v31
	v_cvt_pk_bf16_f32 v199, v32, v33
	ds_write_b64 v1, v[198:199] offset:4640
	s_waitcnt lgkmcnt(7)
	v_and_b32_e32 v3, 0xffff0000, v200
	v_lshlrev_b32_e32 v2, 16, v200
	v_pk_mul_f32 v[34:35], v[34:35], v[2:3]
	v_and_b32_e32 v3, 0xffff0000, v201
	v_lshlrev_b32_e32 v2, 16, v201
	v_pk_mul_f32 v[36:37], v[36:37], v[2:3]
	v_cvt_pk_bf16_f32 v200, v34, v35
	v_cvt_pk_bf16_f32 v201, v36, v37
	ds_write_b64 v1, v[200:201] offset:4656
	s_waitcnt lgkmcnt(7)
	v_and_b32_e32 v3, 0xffff0000, v202
	v_lshlrev_b32_e32 v2, 16, v202
	v_pk_mul_f32 v[6:7], v[6:7], v[2:3]
	v_and_b32_e32 v3, 0xffff0000, v203
	v_lshlrev_b32_e32 v2, 16, v203
	v_pk_mul_f32 v[8:9], v[8:9], v[2:3]
	v_cvt_pk_bf16_f32 v202, v6, v7
	v_cvt_pk_bf16_f32 v203, v8, v9
	ds_write_b64 v1, v[202:203] offset:4672
	s_waitcnt lgkmcnt(7)
	v_and_b32_e32 v3, 0xffff0000, v204
	v_lshlrev_b32_e32 v2, 16, v204
	v_pk_mul_f32 v[10:11], v[10:11], v[2:3]
	v_and_b32_e32 v3, 0xffff0000, v205
	v_lshlrev_b32_e32 v2, 16, v205
	v_pk_mul_f32 v[12:13], v[12:13], v[2:3]
	v_cvt_pk_bf16_f32 v204, v10, v11
	v_cvt_pk_bf16_f32 v205, v12, v13
	ds_write_b64 v1, v[204:205] offset:4688
	s_waitcnt lgkmcnt(7)
	v_and_b32_e32 v3, 0xffff0000, v206
	v_lshlrev_b32_e32 v2, 16, v206
	v_pk_mul_f32 v[14:15], v[14:15], v[2:3]
	v_and_b32_e32 v3, 0xffff0000, v207
	v_lshlrev_b32_e32 v2, 16, v207
	v_pk_mul_f32 v[16:17], v[16:17], v[2:3]
	v_cvt_pk_bf16_f32 v206, v14, v15
	v_cvt_pk_bf16_f32 v207, v16, v17
	ds_write_b64 v1, v[206:207] offset:4704
	s_waitcnt lgkmcnt(7)
	v_and_b32_e32 v3, 0xffff0000, v208
	v_lshlrev_b32_e32 v2, 16, v208
	v_pk_mul_f32 v[18:19], v[18:19], v[2:3]
	v_and_b32_e32 v3, 0xffff0000, v209
	v_lshlrev_b32_e32 v2, 16, v209
	v_pk_mul_f32 v[20:21], v[20:21], v[2:3]
	v_cvt_pk_bf16_f32 v208, v18, v19
	v_cvt_pk_bf16_f32 v209, v20, v21
	ds_write_b64 v1, v[208:209] offset:4720
	s_waitcnt lgkmcnt(7)
	ds_read_b128 v[178:181], v0
	ds_read_b128 v[182:185], v0 offset:1152
	ds_read_b128 v[186:189], v0 offset:2304
	ds_read_b128 v[190:193], v0 offset:3456
	ds_read_b128 v[194:197], v0 offset:4608
	ds_read_b128 v[198:201], v0 offset:5760
	ds_read_b128 v[202:205], v0 offset:6912
	ds_read_b128 v[206:209], v0 offset:8064
	s_add_u32 s74, s72, 0x20000
	s_addc_u32 s75, s73, 0
	s_waitcnt lgkmcnt(7)
	global_store_dwordx4 v5, v[178:181], s[74:75]
	s_add_u32 s74, s72, 0x24000
	s_addc_u32 s75, s73, 0
	s_waitcnt lgkmcnt(6)
	global_store_dwordx4 v5, v[182:185], s[74:75]
	s_add_u32 s74, s72, 0x28000
	s_addc_u32 s75, s73, 0
	s_waitcnt lgkmcnt(5)
	global_store_dwordx4 v5, v[186:189], s[74:75]
	s_add_u32 s74, s72, 0x2c000
	s_addc_u32 s75, s73, 0
	s_waitcnt lgkmcnt(4)
	global_store_dwordx4 v5, v[190:193], s[74:75]
	s_add_u32 s74, s72, 0x30000
	s_addc_u32 s75, s73, 0
	s_waitcnt lgkmcnt(3)
	global_store_dwordx4 v5, v[194:197], s[74:75]
	s_add_u32 s74, s72, 0x34000
	s_addc_u32 s75, s73, 0
	s_waitcnt lgkmcnt(2)
	global_store_dwordx4 v5, v[198:201], s[74:75]
	s_add_u32 s74, s72, 0x38000
	s_addc_u32 s75, s73, 0
	s_waitcnt lgkmcnt(1)
	global_store_dwordx4 v5, v[202:205], s[74:75]
	s_add_u32 s74, s72, 0x3c000
	s_addc_u32 s75, s73, 0
	s_waitcnt lgkmcnt(0)
	global_store_dwordx4 v5, v[206:209], s[74:75]
	s_branch .Lgepi_done
.Lgepi_scale:
	global_load_dwordx4 v[210:213], v3, s[0:1]
	global_load_dwordx4 v[214:217], v3, s[0:1] offset:32
	global_load_dwordx4 v[218:221], v3, s[0:1] offset:64
	global_load_dwordx4 v[222:225], v3, s[0:1] offset:96
	global_load_dwordx4 v[226:229], v3, s[0:1] offset:128
	global_load_dwordx4 v[230:233], v3, s[0:1] offset:160
	global_load_dwordx4 v[234:237], v3, s[0:1] offset:192
	global_load_dwordx4 v[134:137], v3, s[0:1] offset:224
	s_add_u32 s74, s70, 0x0
	s_addc_u32 s75, s71, 0
	global_load_dwordx4 v[146:149], v2, s[74:75]
	s_add_u32 s74, s70, 0x5000
	s_addc_u32 s75, s71, 0
	global_load_dwordx4 v[150:153], v2, s[74:75]
	s_add_u32 s74, s70, 0xa000
	s_addc_u32 s75, s71, 0
	global_load_dwordx4 v[154:157], v2, s[74:75]
	s_add_u32 s74, s70, 0xf000
	s_addc_u32 s75, s71, 0
	global_load_dwordx4 v[158:161], v2, s[74:75]
	s_add_u32 s74, s70, 0x14000
	s_addc_u32 s75, s71, 0
	global_load_dwordx4 v[162:165], v2, s[74:75]
	s_add_u32 s74, s70, 0x19000
	s_addc_u32 s75, s71, 0
	global_load_dwordx4 v[166:169], v2, s[74:75]
	s_add_u32 s74, s70, 0x1e000
	s_addc_u32 s75, s71, 0
	global_load_dwordx4 v[170:173], v2, s[74:75]
	s_add_u32 s74, s70, 0x23000
	s_addc_u32 s75, s71, 0
	global_load_dwordx4 v[174:177], v2, s[74:75]
	s_add_u32 s74, s70, 0x28000
	s_addc_u32 s75, s71, 0
	global_load_dwordx4 v[178:181], v2, s[74:75]
	s_add_u32 s74, s70, 0x2d000
	s_addc_u32 s75, s71, 0
	global_load_dwordx4 v[182:185], v2, s[74:75]
	s_add_u32 s74, s70, 0x32000
	s_addc_u32 s75, s71, 0
	global_load_dwordx4 v[186:189], v2, s[74:75]
	s_add_u32 s74, s70, 0x37000
	s_addc_u32 s75, s71, 0
	global_load_dwordx4 v[190:193], v2, s[74:75]
	s_add_u32 s74, s70, 0x3c000
	s_addc_u32 s75, s71, 0
	global_load_dwordx4 v[194:197], v2, s[74:75]
	s_add_u32 s74, s70, 0x41000
	s_addc_u32 s75, s71, 0
	global_load_dwordx4 v[198:201], v2, s[74:75]
	s_add_u32 s74, s70, 0x46000
	s_addc_u32 s75, s71, 0
	global_load_dwordx4 v[202:205], v2, s[74:75]
	s_add_u32 s74, s70, 0x4b000
	s_addc_u32 s75, s71, 0
	global_load_dwordx4 v[206:209], v2, s[74:75]
	s_waitcnt vmcnt(15)
	ds_write_b128 v0, v[146:149]
	s_waitcnt vmcnt(14)
	ds_write_b128 v0, v[150:153] offset:1152
	s_waitcnt vmcnt(13)
	ds_write_b128 v0, v[154:157] offset:2304
	s_waitcnt vmcnt(12)
	ds_write_b128 v0, v[158:161] offset:3456
	s_waitcnt vmcnt(11)
	ds_write_b128 v0, v[162:165] offset:4608
	s_waitcnt vmcnt(10)
	ds_write_b128 v0, v[166:169] offset:5760
	s_waitcnt vmcnt(9)
	ds_write_b128 v0, v[170:173] offset:6912
	s_waitcnt vmcnt(8)
	ds_write_b128 v0, v[174:177] offset:8064
	s_waitcnt lgkmcnt(7)
	ds_read_b64 v[146:147], v1
	ds_read_b64 v[148:149], v1 offset:16
	ds_read_b64 v[150:151], v1 offset:32
	ds_read_b64 v[152:153], v1 offset:48
	ds_read_b64 v[154:155], v1 offset:64
	ds_read_b64 v[156:157], v1 offset:80
	ds_read_b64 v[158:159], v1 offset:96
	ds_read_b64 v[160:161], v1 offset:112
	s_waitcnt lgkmcnt(7)
	v_pk_mul_f32 v[118:119], v[118:119], v[210:211]
	v_pk_mul_f32 v[120:121], v[120:121], v[212:213]
	v_and_b32_e32 v3, 0xffff0000, v146
	v_lshlrev_b32_e32 v2, 16, v146
	v_pk_mul_f32 v[118:119], v[118:119], v[2:3]
	v_and_b32_e32 v3, 0xffff0000, v147
	v_lshlrev_b32_e32 v2, 16, v147
	v_pk_mul_f32 v[120:121], v[120:121], v[2:3]
	v_cvt_pk_bf16_f32 v146, v118, v119
	v_cvt_pk_bf16_f32 v147, v120, v121
	ds_write_b64 v1, v[146:147]
	s_waitcnt lgkmcnt(7)
	v_pk_mul_f32 v[122:123], v[122:123], v[214:215]
	v_pk_mul_f32 v[124:125], v[124:125], v[216:217]
	v_and_b32_e32 v3, 0xffff0000, v148
	v_lshlrev_b32_e32 v2, 16, v148
	v_pk_mul_f32 v[122:123], v[122:123], v[2:3]
	v_and_b32_e32 v3, 0xffff0000, v149
	v_lshlrev_b32_e32 v2, 16, v149
	v_pk_mul_f32 v[124:125], v[124:125], v[2:3]
	v_cvt_pk_bf16_f32 v148, v122, v123
	v_cvt_pk_bf16_f32 v149, v124, v125
	ds_write_b64 v1, v[148:149] offset:16
	s_waitcnt lgkmcnt(7)
	v_pk_mul_f32 v[126:127], v[126:127], v[218:219]
	v_pk_mul_f32 v[128:129], v[128:129], v[220:221]
	v_and_b32_e32 v3, 0xffff0000, v150
	v_lshlrev_b32_e32 v2, 16, v150
	v_pk_mul_f32 v[126:127], v[126:127], v[2:3]
	v_and_b32_e32 v3, 0xffff0000, v151
	v_lshlrev_b32_e32 v2, 16, v151
	v_pk_mul_f32 v[128:129], v[128:129], v[2:3]
	v_cvt_pk_bf16_f32 v150, v126, v127
	v_cvt_pk_bf16_f32 v151, v128, v129
	ds_write_b64 v1, v[150:151] offset:32
	s_waitcnt lgkmcnt(7)
	v_pk_mul_f32 v[130:131], v[130:131], v[222:223]
	v_pk_mul_f32 v[132:133], v[132:133], v[224:225]
	v_and_b32_e32 v3, 0xffff0000, v152
	v_lshlrev_b32_e32 v2, 16, v152
	v_pk_mul_f32 v[130:131], v[130:131], v[2:3]
	v_and_b32_e32 v3, 0xffff0000, v153
	v_lshlrev_b32_e32 v2, 16, v153
	v_pk_mul_f32 v[132:133], v[132:133], v[2:3]
	v_cvt_pk_bf16_f32 v152, v130, v131
	v_cvt_pk_bf16_f32 v153, v132, v133
	ds_write_b64 v1, v[152:153] offset:48
	s_waitcnt lgkmcnt(7)
	v_pk_mul_f32 v[102:103], v[102:103], v[226:227]
	v_pk_mul_f32 v[104:105], v[104:105], v[228:229]
	v_and_b32_e32 v3, 0xffff0000, v154
	v_lshlrev_b32_e32 v2, 16, v154
	v_pk_mul_f32 v[102:103], v[102:103], v[2:3]
	v_and_b32_e32 v3, 0xffff0000, v155
	v_lshlrev_b32_e32 v2, 16, v155
	v_pk_mul_f32 v[104:105], v[104:105], v[2:3]
	v_cvt_pk_bf16_f32 v154, v102, v103
	v_cvt_pk_bf16_f32 v155, v104, v105
	ds_write_b64 v1, v[154:155] offset:64
	s_waitcnt lgkmcnt(7)
	v_pk_mul_f32 v[106:107], v[106:107], v[230:231]
	v_pk_mul_f32 v[108:109], v[108:109], v[232:233]
	v_and_b32_e32 v3, 0xffff0000, v156
	v_lshlrev_b32_e32 v2, 16, v156
	v_pk_mul_f32 v[106:107], v[106:107], v[2:3]
	v_and_b32_e32 v3, 0xffff0000, v157
	v_lshlrev_b32_e32 v2, 16, v157
	v_pk_mul_f32 v[108:109], v[108:109], v[2:3]
	v_cvt_pk_bf16_f32 v156, v106, v107
	v_cvt_pk_bf16_f32 v157, v108, v109
	ds_write_b64 v1, v[156:157] offset:80
	s_waitcnt lgkmcnt(7)
	v_pk_mul_f32 v[110:111], v[110:111], v[234:235]
	v_pk_mul_f32 v[112:113], v[112:113], v[236:237]
	v_and_b32_e32 v3, 0xffff0000, v158
	v_lshlrev_b32_e32 v2, 16, v158
	v_pk_mul_f32 v[110:111], v[110:111], v[2:3]
	v_and_b32_e32 v3, 0xffff0000, v159
	v_lshlrev_b32_e32 v2, 16, v159
	v_pk_mul_f32 v[112:113], v[112:113], v[2:3]
	v_cvt_pk_bf16_f32 v158, v110, v111
	v_cvt_pk_bf16_f32 v159, v112, v113
	ds_write_b64 v1, v[158:159] offset:96
	s_waitcnt lgkmcnt(7)
	v_pk_mul_f32 v[114:115], v[114:115], v[134:135]
	v_pk_mul_f32 v[116:117], v[116:117], v[136:137]
	v_and_b32_e32 v3, 0xffff0000, v160
	v_lshlrev_b32_e32 v2, 16, v160
	v_pk_mul_f32 v[114:115], v[114:115], v[2:3]
	v_and_b32_e32 v3, 0xffff0000, v161
	v_lshlrev_b32_e32 v2, 16, v161
	v_pk_mul_f32 v[116:117], v[116:117], v[2:3]
	v_cvt_pk_bf16_f32 v160, v114, v115
	v_cvt_pk_bf16_f32 v161, v116, v117
	ds_write_b64 v1, v[160:161] offset:112
	s_waitcnt lgkmcnt(7)
	ds_read_b64 v[162:163], v1 offset:4608
	ds_read_b64 v[164:165], v1 offset:4624
	ds_read_b64 v[166:167], v1 offset:4640
	ds_read_b64 v[168:169], v1 offset:4656
	ds_read_b64 v[170:171], v1 offset:4672
	ds_read_b64 v[172:173], v1 offset:4688
	ds_read_b64 v[174:175], v1 offset:4704
	ds_read_b64 v[176:177], v1 offset:4720
	s_waitcnt lgkmcnt(7)
	v_pk_mul_f32 v[86:87], v[86:87], v[210:211]
	v_pk_mul_f32 v[88:89], v[88:89], v[212:213]
	v_and_b32_e32 v3, 0xffff0000, v162
	v_lshlrev_b32_e32 v2, 16, v162
	v_pk_mul_f32 v[86:87], v[86:87], v[2:3]
	v_and_b32_e32 v3, 0xffff0000, v163
	v_lshlrev_b32_e32 v2, 16, v163
	v_pk_mul_f32 v[88:89], v[88:89], v[2:3]
	v_cvt_pk_bf16_f32 v162, v86, v87
	v_cvt_pk_bf16_f32 v163, v88, v89
	ds_write_b64 v1, v[162:163] offset:4608
	s_waitcnt lgkmcnt(7)
	v_pk_mul_f32 v[90:91], v[90:91], v[214:215]
	v_pk_mul_f32 v[92:93], v[92:93], v[216:217]
	v_and_b32_e32 v3, 0xffff0000, v164
	v_lshlrev_b32_e32 v2, 16, v164
	v_pk_mul_f32 v[90:91], v[90:91], v[2:3]
	v_and_b32_e32 v3, 0xffff0000, v165
	v_lshlrev_b32_e32 v2, 16, v165
	v_pk_mul_f32 v[92:93], v[92:93], v[2:3]
	v_cvt_pk_bf16_f32 v164, v90, v91
	v_cvt_pk_bf16_f32 v165, v92, v93
	ds_write_b64 v1, v[164:165] offset:4624
	s_waitcnt lgkmcnt(7)
	v_pk_mul_f32 v[94:95], v[94:95], v[218:219]
	v_pk_mul_f32 v[96:97], v[96:97], v[220:221]
	v_and_b32_e32 v3, 0xffff0000, v166
	v_lshlrev_b32_e32 v2, 16, v166
	v_pk_mul_f32 v[94:95], v[94:95], v[2:3]
	v_and_b32_e32 v3, 0xffff0000, v167
	v_lshlrev_b32_e32 v2, 16, v167
	v_pk_mul_f32 v[96:97], v[96:97], v[2:3]
	v_cvt_pk_bf16_f32 v166, v94, v95
	v_cvt_pk_bf16_f32 v167, v96, v97
	ds_write_b64 v1, v[166:167] offset:4640
	s_waitcnt lgkmcnt(7)
	v_pk_mul_f32 v[98:99], v[98:99], v[222:223]
	v_pk_mul_f32 v[100:101], v[100:101], v[224:225]
	v_and_b32_e32 v3, 0xffff0000, v168
	v_lshlrev_b32_e32 v2, 16, v168
	v_pk_mul_f32 v[98:99], v[98:99], v[2:3]
	v_and_b32_e32 v3, 0xffff0000, v169
	v_lshlrev_b32_e32 v2, 16, v169
	v_pk_mul_f32 v[100:101], v[100:101], v[2:3]
	v_cvt_pk_bf16_f32 v168, v98, v99
	v_cvt_pk_bf16_f32 v169, v100, v101
	ds_write_b64 v1, v[168:169] offset:4656
	s_waitcnt lgkmcnt(7)
	v_pk_mul_f32 v[70:71], v[70:71], v[226:227]
	v_pk_mul_f32 v[72:73], v[72:73], v[228:229]
	v_and_b32_e32 v3, 0xffff0000, v170
	v_lshlrev_b32_e32 v2, 16, v170
	v_pk_mul_f32 v[70:71], v[70:71], v[2:3]
	v_and_b32_e32 v3, 0xffff0000, v171
	v_lshlrev_b32_e32 v2, 16, v171
	v_pk_mul_f32 v[72:73], v[72:73], v[2:3]
	v_cvt_pk_bf16_f32 v170, v70, v71
	v_cvt_pk_bf16_f32 v171, v72, v73
	ds_write_b64 v1, v[170:171] offset:4672
	s_waitcnt lgkmcnt(7)
	v_pk_mul_f32 v[74:75], v[74:75], v[230:231]
	v_pk_mul_f32 v[76:77], v[76:77], v[232:233]
	v_and_b32_e32 v3, 0xffff0000, v172
	v_lshlrev_b32_e32 v2, 16, v172
	v_pk_mul_f32 v[74:75], v[74:75], v[2:3]
	v_and_b32_e32 v3, 0xffff0000, v173
	v_lshlrev_b32_e32 v2, 16, v173
	v_pk_mul_f32 v[76:77], v[76:77], v[2:3]
	v_cvt_pk_bf16_f32 v172, v74, v75
	v_cvt_pk_bf16_f32 v173, v76, v77
	ds_write_b64 v1, v[172:173] offset:4688
	s_waitcnt lgkmcnt(7)
	v_pk_mul_f32 v[78:79], v[78:79], v[234:235]
	v_pk_mul_f32 v[80:81], v[80:81], v[236:237]
	v_and_b32_e32 v3, 0xffff0000, v174
	v_lshlrev_b32_e32 v2, 16, v174
	v_pk_mul_f32 v[78:79], v[78:79], v[2:3]
	v_and_b32_e32 v3, 0xffff0000, v175
	v_lshlrev_b32_e32 v2, 16, v175
	v_pk_mul_f32 v[80:81], v[80:81], v[2:3]
	v_cvt_pk_bf16_f32 v174, v78, v79
	v_cvt_pk_bf16_f32 v175, v80, v81
	ds_write_b64 v1, v[174:175] offset:4704
	s_waitcnt lgkmcnt(7)
	v_pk_mul_f32 v[82:83], v[82:83], v[134:135]
	v_pk_mul_f32 v[84:85], v[84:85], v[136:137]
	v_and_b32_e32 v3, 0xffff0000, v176
	v_lshlrev_b32_e32 v2, 16, v176
	v_pk_mul_f32 v[82:83], v[82:83], v[2:3]
	v_and_b32_e32 v3, 0xffff0000, v177
	v_lshlrev_b32_e32 v2, 16, v177
	v_pk_mul_f32 v[84:85], v[84:85], v[2:3]
	v_cvt_pk_bf16_f32 v176, v82, v83
	v_cvt_pk_bf16_f32 v177, v84, v85
	ds_write_b64 v1, v[176:177] offset:4720
	s_waitcnt lgkmcnt(7)
	ds_read_b128 v[146:149], v0
	ds_read_b128 v[150:153], v0 offset:1152
	ds_read_b128 v[154:157], v0 offset:2304
	ds_read_b128 v[158:161], v0 offset:3456
	ds_read_b128 v[162:165], v0 offset:4608
	ds_read_b128 v[166:169], v0 offset:5760
	ds_read_b128 v[170:173], v0 offset:6912
	ds_read_b128 v[174:177], v0 offset:8064
	s_add_u32 s74, s72, 0x0
	s_addc_u32 s75, s73, 0
	s_waitcnt lgkmcnt(7)
	global_store_dwordx4 v5, v[146:149], s[74:75]
	s_add_u32 s74, s72, 0x4000
	s_addc_u32 s75, s73, 0
	s_waitcnt lgkmcnt(6)
	global_store_dwordx4 v5, v[150:153], s[74:75]
	s_add_u32 s74, s72, 0x8000
	s_addc_u32 s75, s73, 0
	s_waitcnt lgkmcnt(5)
	global_store_dwordx4 v5, v[154:157], s[74:75]
	s_add_u32 s74, s72, 0xc000
	s_addc_u32 s75, s73, 0
	s_waitcnt lgkmcnt(4)
	global_store_dwordx4 v5, v[158:161], s[74:75]
	s_add_u32 s74, s72, 0x10000
	s_addc_u32 s75, s73, 0
	s_waitcnt lgkmcnt(3)
	global_store_dwordx4 v5, v[162:165], s[74:75]
	s_add_u32 s74, s72, 0x14000
	s_addc_u32 s75, s73, 0
	s_waitcnt lgkmcnt(2)
	global_store_dwordx4 v5, v[166:169], s[74:75]
	s_add_u32 s74, s72, 0x18000
	s_addc_u32 s75, s73, 0
	s_waitcnt lgkmcnt(1)
	global_store_dwordx4 v5, v[170:173], s[74:75]
	s_add_u32 s74, s72, 0x1c000
	s_addc_u32 s75, s73, 0
	s_waitcnt lgkmcnt(0)
	global_store_dwordx4 v5, v[174:177], s[74:75]
	s_waitcnt vmcnt(15)
	ds_write_b128 v0, v[178:181]
	s_waitcnt vmcnt(14)
	ds_write_b128 v0, v[182:185] offset:1152
	s_waitcnt vmcnt(13)
	ds_write_b128 v0, v[186:189] offset:2304
	s_waitcnt vmcnt(12)
	ds_write_b128 v0, v[190:193] offset:3456
	s_waitcnt vmcnt(11)
	ds_write_b128 v0, v[194:197] offset:4608
	s_waitcnt vmcnt(10)
	ds_write_b128 v0, v[198:201] offset:5760
	s_waitcnt vmcnt(9)
	ds_write_b128 v0, v[202:205] offset:6912
	s_waitcnt vmcnt(8)
	ds_write_b128 v0, v[206:209] offset:8064
	s_waitcnt lgkmcnt(7)
	ds_read_b64 v[178:179], v1
	ds_read_b64 v[180:181], v1 offset:16
	ds_read_b64 v[182:183], v1 offset:32
	ds_read_b64 v[184:185], v1 offset:48
	ds_read_b64 v[186:187], v1 offset:64
	ds_read_b64 v[188:189], v1 offset:80
	ds_read_b64 v[190:191], v1 offset:96
	ds_read_b64 v[192:193], v1 offset:112
	s_waitcnt lgkmcnt(7)
	v_pk_mul_f32 v[54:55], v[54:55], v[210:211]
	v_pk_mul_f32 v[56:57], v[56:57], v[212:213]
	v_and_b32_e32 v3, 0xffff0000, v178
	v_lshlrev_b32_e32 v2, 16, v178
	v_pk_mul_f32 v[54:55], v[54:55], v[2:3]
	v_and_b32_e32 v3, 0xffff0000, v179
	v_lshlrev_b32_e32 v2, 16, v179
	v_pk_mul_f32 v[56:57], v[56:57], v[2:3]
	v_cvt_pk_bf16_f32 v178, v54, v55
	v_cvt_pk_bf16_f32 v179, v56, v57
	ds_write_b64 v1, v[178:179]
	s_waitcnt lgkmcnt(7)
	v_pk_mul_f32 v[58:59], v[58:59], v[214:215]
	v_pk_mul_f32 v[60:61], v[60:61], v[216:217]
	v_and_b32_e32 v3, 0xffff0000, v180
	v_lshlrev_b32_e32 v2, 16, v180
	v_pk_mul_f32 v[58:59], v[58:59], v[2:3]
	v_and_b32_e32 v3, 0xffff0000, v181
	v_lshlrev_b32_e32 v2, 16, v181
	v_pk_mul_f32 v[60:61], v[60:61], v[2:3]
	v_cvt_pk_bf16_f32 v180, v58, v59
	v_cvt_pk_bf16_f32 v181, v60, v61
	ds_write_b64 v1, v[180:181] offset:16
	s_waitcnt lgkmcnt(7)
	v_pk_mul_f32 v[62:63], v[62:63], v[218:219]
	v_pk_mul_f32 v[64:65], v[64:65], v[220:221]
	v_and_b32_e32 v3, 0xffff0000, v182
	v_lshlrev_b32_e32 v2, 16, v182
	v_pk_mul_f32 v[62:63], v[62:63], v[2:3]
	v_and_b32_e32 v3, 0xffff0000, v183
	v_lshlrev_b32_e32 v2, 16, v183
	v_pk_mul_f32 v[64:65], v[64:65], v[2:3]
	v_cvt_pk_bf16_f32 v182, v62, v63
	v_cvt_pk_bf16_f32 v183, v64, v65
	ds_write_b64 v1, v[182:183] offset:32
	s_waitcnt lgkmcnt(7)
	v_pk_mul_f32 v[66:67], v[66:67], v[222:223]
	v_pk_mul_f32 v[68:69], v[68:69], v[224:225]
	v_and_b32_e32 v3, 0xffff0000, v184
	v_lshlrev_b32_e32 v2, 16, v184
	v_pk_mul_f32 v[66:67], v[66:67], v[2:3]
	v_and_b32_e32 v3, 0xffff0000, v185
	v_lshlrev_b32_e32 v2, 16, v185
	v_pk_mul_f32 v[68:69], v[68:69], v[2:3]
	v_cvt_pk_bf16_f32 v184, v66, v67
	v_cvt_pk_bf16_f32 v185, v68, v69
	ds_write_b64 v1, v[184:185] offset:48
	s_waitcnt lgkmcnt(7)
	v_pk_mul_f32 v[38:39], v[38:39], v[226:227]
	v_pk_mul_f32 v[40:41], v[40:41], v[228:229]
	v_and_b32_e32 v3, 0xffff0000, v186
	v_lshlrev_b32_e32 v2, 16, v186
	v_pk_mul_f32 v[38:39], v[38:39], v[2:3]
	v_and_b32_e32 v3, 0xffff0000, v187
	v_lshlrev_b32_e32 v2, 16, v187
	v_pk_mul_f32 v[40:41], v[40:41], v[2:3]
	v_cvt_pk_bf16_f32 v186, v38, v39
	v_cvt_pk_bf16_f32 v187, v40, v41
	ds_write_b64 v1, v[186:187] offset:64
	s_waitcnt lgkmcnt(7)
	v_pk_mul_f32 v[42:43], v[42:43], v[230:231]
	v_pk_mul_f32 v[44:45], v[44:45], v[232:233]
	v_and_b32_e32 v3, 0xffff0000, v188
	v_lshlrev_b32_e32 v2, 16, v188
	v_pk_mul_f32 v[42:43], v[42:43], v[2:3]
	v_and_b32_e32 v3, 0xffff0000, v189
	v_lshlrev_b32_e32 v2, 16, v189
	v_pk_mul_f32 v[44:45], v[44:45], v[2:3]
	v_cvt_pk_bf16_f32 v188, v42, v43
	v_cvt_pk_bf16_f32 v189, v44, v45
	ds_write_b64 v1, v[188:189] offset:80
	s_waitcnt lgkmcnt(7)
	v_pk_mul_f32 v[46:47], v[46:47], v[234:235]
	v_pk_mul_f32 v[48:49], v[48:49], v[236:237]
	v_and_b32_e32 v3, 0xffff0000, v190
	v_lshlrev_b32_e32 v2, 16, v190
	v_pk_mul_f32 v[46:47], v[46:47], v[2:3]
	v_and_b32_e32 v3, 0xffff0000, v191
	v_lshlrev_b32_e32 v2, 16, v191
	v_pk_mul_f32 v[48:49], v[48:49], v[2:3]
	v_cvt_pk_bf16_f32 v190, v46, v47
	v_cvt_pk_bf16_f32 v191, v48, v49
	ds_write_b64 v1, v[190:191] offset:96
	s_waitcnt lgkmcnt(7)
	v_pk_mul_f32 v[50:51], v[50:51], v[134:135]
	v_pk_mul_f32 v[52:53], v[52:53], v[136:137]
	v_and_b32_e32 v3, 0xffff0000, v192
	v_lshlrev_b32_e32 v2, 16, v192
	v_pk_mul_f32 v[50:51], v[50:51], v[2:3]
	v_and_b32_e32 v3, 0xffff0000, v193
	v_lshlrev_b32_e32 v2, 16, v193
	v_pk_mul_f32 v[52:53], v[52:53], v[2:3]
	v_cvt_pk_bf16_f32 v192, v50, v51
	v_cvt_pk_bf16_f32 v193, v52, v53
	ds_write_b64 v1, v[192:193] offset:112
	s_waitcnt lgkmcnt(7)
	ds_read_b64 v[194:195], v1 offset:4608
	ds_read_b64 v[196:197], v1 offset:4624
	ds_read_b64 v[198:199], v1 offset:4640
	ds_read_b64 v[200:201], v1 offset:4656
	ds_read_b64 v[202:203], v1 offset:4672
	ds_read_b64 v[204:205], v1 offset:4688
	ds_read_b64 v[206:207], v1 offset:4704
	ds_read_b64 v[208:209], v1 offset:4720
	s_waitcnt lgkmcnt(7)
	v_pk_mul_f32 v[22:23], v[22:23], v[210:211]
	v_pk_mul_f32 v[24:25], v[24:25], v[212:213]
	v_and_b32_e32 v3, 0xffff0000, v194
	v_lshlrev_b32_e32 v2, 16, v194
	v_pk_mul_f32 v[22:23], v[22:23], v[2:3]
	v_and_b32_e32 v3, 0xffff0000, v195
	v_lshlrev_b32_e32 v2, 16, v195
	v_pk_mul_f32 v[24:25], v[24:25], v[2:3]
	v_cvt_pk_bf16_f32 v194, v22, v23
	v_cvt_pk_bf16_f32 v195, v24, v25
	ds_write_b64 v1, v[194:195] offset:4608
	s_waitcnt lgkmcnt(7)
	v_pk_mul_f32 v[26:27], v[26:27], v[214:215]
	v_pk_mul_f32 v[28:29], v[28:29], v[216:217]
	v_and_b32_e32 v3, 0xffff0000, v196
	v_lshlrev_b32_e32 v2, 16, v196
	v_pk_mul_f32 v[26:27], v[26:27], v[2:3]
	v_and_b32_e32 v3, 0xffff0000, v197
	v_lshlrev_b32_e32 v2, 16, v197
	v_pk_mul_f32 v[28:29], v[28:29], v[2:3]
	v_cvt_pk_bf16_f32 v196, v26, v27
	v_cvt_pk_bf16_f32 v197, v28, v29
	ds_write_b64 v1, v[196:197] offset:4624
	s_waitcnt lgkmcnt(7)
	v_pk_mul_f32 v[30:31], v[30:31], v[218:219]
	v_pk_mul_f32 v[32:33], v[32:33], v[220:221]
	v_and_b32_e32 v3, 0xffff0000, v198
	v_lshlrev_b32_e32 v2, 16, v198
	v_pk_mul_f32 v[30:31], v[30:31], v[2:3]
	v_and_b32_e32 v3, 0xffff0000, v199
	v_lshlrev_b32_e32 v2, 16, v199
	v_pk_mul_f32 v[32:33], v[32:33], v[2:3]
	v_cvt_pk_bf16_f32 v198, v30, v31
	v_cvt_pk_bf16_f32 v199, v32, v33
	ds_write_b64 v1, v[198:199] offset:4640
	s_waitcnt lgkmcnt(7)
	v_pk_mul_f32 v[34:35], v[34:35], v[222:223]
	v_pk_mul_f32 v[36:37], v[36:37], v[224:225]
	v_and_b32_e32 v3, 0xffff0000, v200
	v_lshlrev_b32_e32 v2, 16, v200
	v_pk_mul_f32 v[34:35], v[34:35], v[2:3]
	v_and_b32_e32 v3, 0xffff0000, v201
	v_lshlrev_b32_e32 v2, 16, v201
	v_pk_mul_f32 v[36:37], v[36:37], v[2:3]
	v_cvt_pk_bf16_f32 v200, v34, v35
	v_cvt_pk_bf16_f32 v201, v36, v37
	ds_write_b64 v1, v[200:201] offset:4656
	s_waitcnt lgkmcnt(7)
	v_pk_mul_f32 v[6:7], v[6:7], v[226:227]
	v_pk_mul_f32 v[8:9], v[8:9], v[228:229]
	v_and_b32_e32 v3, 0xffff0000, v202
	v_lshlrev_b32_e32 v2, 16, v202
	v_pk_mul_f32 v[6:7], v[6:7], v[2:3]
	v_and_b32_e32 v3, 0xffff0000, v203
	v_lshlrev_b32_e32 v2, 16, v203
	v_pk_mul_f32 v[8:9], v[8:9], v[2:3]
	v_cvt_pk_bf16_f32 v202, v6, v7
	v_cvt_pk_bf16_f32 v203, v8, v9
	ds_write_b64 v1, v[202:203] offset:4672
	s_waitcnt lgkmcnt(7)
	v_pk_mul_f32 v[10:11], v[10:11], v[230:231]
	v_pk_mul_f32 v[12:13], v[12:13], v[232:233]
	v_and_b32_e32 v3, 0xffff0000, v204
	v_lshlrev_b32_e32 v2, 16, v204
	v_pk_mul_f32 v[10:11], v[10:11], v[2:3]
	v_and_b32_e32 v3, 0xffff0000, v205
	v_lshlrev_b32_e32 v2, 16, v205
	v_pk_mul_f32 v[12:13], v[12:13], v[2:3]
	v_cvt_pk_bf16_f32 v204, v10, v11
	v_cvt_pk_bf16_f32 v205, v12, v13
	ds_write_b64 v1, v[204:205] offset:4688
	s_waitcnt lgkmcnt(7)
	v_pk_mul_f32 v[14:15], v[14:15], v[234:235]
	v_pk_mul_f32 v[16:17], v[16:17], v[236:237]
	v_and_b32_e32 v3, 0xffff0000, v206
	v_lshlrev_b32_e32 v2, 16, v206
	v_pk_mul_f32 v[14:15], v[14:15], v[2:3]
	v_and_b32_e32 v3, 0xffff0000, v207
	v_lshlrev_b32_e32 v2, 16, v207
	v_pk_mul_f32 v[16:17], v[16:17], v[2:3]
	v_cvt_pk_bf16_f32 v206, v14, v15
	v_cvt_pk_bf16_f32 v207, v16, v17
	ds_write_b64 v1, v[206:207] offset:4704
	s_waitcnt lgkmcnt(7)
	v_pk_mul_f32 v[18:19], v[18:19], v[134:135]
	v_pk_mul_f32 v[20:21], v[20:21], v[136:137]
	v_and_b32_e32 v3, 0xffff0000, v208
	v_lshlrev_b32_e32 v2, 16, v208
	v_pk_mul_f32 v[18:19], v[18:19], v[2:3]
	v_and_b32_e32 v3, 0xffff0000, v209
	v_lshlrev_b32_e32 v2, 16, v209
	v_pk_mul_f32 v[20:21], v[20:21], v[2:3]
	v_cvt_pk_bf16_f32 v208, v18, v19
	v_cvt_pk_bf16_f32 v209, v20, v21
	ds_write_b64 v1, v[208:209] offset:4720
	s_waitcnt lgkmcnt(7)
	ds_read_b128 v[178:181], v0
	ds_read_b128 v[182:185], v0 offset:1152
	ds_read_b128 v[186:189], v0 offset:2304
	ds_read_b128 v[190:193], v0 offset:3456
	ds_read_b128 v[194:197], v0 offset:4608
	ds_read_b128 v[198:201], v0 offset:5760
	ds_read_b128 v[202:205], v0 offset:6912
	ds_read_b128 v[206:209], v0 offset:8064
	s_add_u32 s74, s72, 0x20000
	s_addc_u32 s75, s73, 0
	s_waitcnt lgkmcnt(7)
	global_store_dwordx4 v5, v[178:181], s[74:75]
	s_add_u32 s74, s72, 0x24000
	s_addc_u32 s75, s73, 0
	s_waitcnt lgkmcnt(6)
	global_store_dwordx4 v5, v[182:185], s[74:75]
	s_add_u32 s74, s72, 0x28000
	s_addc_u32 s75, s73, 0
	s_waitcnt lgkmcnt(5)
	global_store_dwordx4 v5, v[186:189], s[74:75]
	s_add_u32 s74, s72, 0x2c000
	s_addc_u32 s75, s73, 0
	s_waitcnt lgkmcnt(4)
	global_store_dwordx4 v5, v[190:193], s[74:75]
	s_add_u32 s74, s72, 0x30000
	s_addc_u32 s75, s73, 0
	s_waitcnt lgkmcnt(3)
	global_store_dwordx4 v5, v[194:197], s[74:75]
	s_add_u32 s74, s72, 0x34000
	s_addc_u32 s75, s73, 0
	s_waitcnt lgkmcnt(2)
	global_store_dwordx4 v5, v[198:201], s[74:75]
	s_add_u32 s74, s72, 0x38000
	s_addc_u32 s75, s73, 0
	s_waitcnt lgkmcnt(1)
	global_store_dwordx4 v5, v[202:205], s[74:75]
	s_add_u32 s74, s72, 0x3c000
	s_addc_u32 s75, s73, 0
	s_waitcnt lgkmcnt(0)
	global_store_dwordx4 v5, v[206:209], s[74:75]
